# P0 balance: the 5th rmsnorm row goes to the waves that had only 4 transposing items
# speedup vs baseline: 1.0068x; 1.0034x over previous
; __device__ __forceinline__ void p0_prologue(Frame& F, bool all_weights) {
;     const int gw = F.vcu * NWAVES + F.wave, NGW = F.G * NWAVES;
;     p0_items(F, 0, all_weights ? NITEMS : NITEMS_EARLY, gw, NGW);
;     if (all_weights) { p0_pool_pad(F, F.vcu * NTHR + F.tid, F.G * NTHR); p0_pool_frag(F, F.vcu * NTHR + F.tid, F.G * NTHR); }
;     bf16_t* H = WSP(bf16_t, WS_H); bf16_t* HM = WSP(bf16_t, WS_HM);
;     for (int m = gw; m < MT + MM; m += NGW) {
;         if (m < MP) rms_row_to_bf16(F.in[0] + (size_t)m * DM, F.in[7], H + (size_t)m * DM, F.lane);
;         else if (m < MT) rms_row_to_bf16(F.in[2] + (size_t)(m - MP) * DM, F.in[7], H + (size_t)m * DM, F.lane);
;         else rms_row_to_bf16(F.in[1] + (size_t)(m - MT) * DM, F.in[8], HM + (size_t)(m - MT) * DM, F.lane);
;     }
.LBB0_43:
	s_add_i32 s40, s40, 0x200
	s_and_b32 s40, s40, 0x7ff
	s_cmpk_gt_i32 s40, 0x21ff
	s_cbranch_scc1 .LBB0_54
	v_lshlrev_b32_e32 v2, 4, v1
	v_mov_b32_e32 v3, 0
	s_waitcnt lgkmcnt(0)
	v_lshl_add_u64 v[94:95], s[6:7], 0, v[2:3]
	s_mov_b64 s[6:7], 0x1000
	v_lshl_add_u64 v[120:121], s[4:5], 0, v[2:3]
	v_lshl_add_u64 v[96:97], v[94:95], 0, s[6:7]
	s_mov_b64 s[8:9], 0x1400
	v_lshl_add_u64 v[122:123], v[120:121], 0, s[6:7]
	s_lshl_b32 s6, s12, 16
	s_lshl_b32 s7, s13, 13
	s_ashr_i32 s41, s40, 31
	v_lshl_add_u64 v[98:99], v[94:95], 0, s[8:9]
	v_lshl_add_u64 v[124:125], v[120:121], 0, s[8:9]
	v_mov_b32_e32 v7, v3
	s_add_i32 s6, s6, s7
	s_lshl_b32 s6, s40, 13
	s_lshl_b32 s12, s3, 16
	s_lshl_b64 s[8:9], s[40:41], 13
	v_lshl_add_u64 v[4:5], s[42:43], 0, v[6:7]
	s_mov_b64 s[4:5], 0x1b200000
	s_add_u32 s8, s42, s8
	v_lshl_add_u64 v[148:149], v[4:5], 0, s[4:5]
	s_mov_b64 s[4:5], 0x1ba00000
	s_addc_u32 s9, s43, s9
	v_lshl_add_u64 v[152:153], v[4:5], 0, s[4:5]
	v_lshl_add_u64 v[4:5], s[8:9], 0, v[6:7]
	s_ashr_i32 s29, s28, 31
	v_lshl_add_u64 v[154:155], v[4:5], 0, s[4:5]
	s_lshl_b64 s[8:9], s[28:29], 13
	s_lshl_b64 s[4:5], s[40:41], 14
	s_add_u32 s4, s16, s4
	s_mov_b64 s[10:11], 0x1800
	s_mov_b64 s[20:21], 0x1c00
	s_mov_b64 s[22:23], 0x2000
	s_mov_b64 s[24:25], 0x2400
	s_mov_b64 s[26:27], 0x2800
	s_mov_b64 s[34:35], 0x2c00
	s_mov_b64 s[36:37], 0x3000
	s_mov_b64 s[46:47], 0x3400
	s_mov_b64 s[48:49], 0x3800
	s_mov_b64 s[50:51], 0x3c00
	s_addc_u32 s5, s17, s5
	v_lshl_add_u64 v[100:101], v[94:95], 0, s[10:11]
	v_lshl_add_u64 v[102:103], v[94:95], 0, s[20:21]
	v_lshl_add_u64 v[104:105], v[94:95], 0, s[22:23]
	v_lshl_add_u64 v[106:107], v[94:95], 0, s[24:25]
	v_lshl_add_u64 v[108:109], v[94:95], 0, s[26:27]
	v_lshl_add_u64 v[110:111], v[94:95], 0, s[34:35]
	v_lshl_add_u64 v[112:113], v[94:95], 0, s[36:37]
	v_lshl_add_u64 v[114:115], v[94:95], 0, s[46:47]
	v_lshl_add_u64 v[116:117], v[94:95], 0, s[48:49]
	v_lshl_add_u64 v[118:119], v[94:95], 0, s[50:51]
	v_lshl_add_u64 v[126:127], v[120:121], 0, s[10:11]
	v_lshl_add_u64 v[128:129], v[120:121], 0, s[20:21]
	v_lshl_add_u64 v[130:131], v[120:121], 0, s[22:23]
	v_lshl_add_u64 v[132:133], v[120:121], 0, s[24:25]
	v_lshl_add_u64 v[134:135], v[120:121], 0, s[26:27]
	v_lshl_add_u64 v[136:137], v[120:121], 0, s[34:35]
	v_lshl_add_u64 v[138:139], v[120:121], 0, s[36:37]
	v_lshl_add_u64 v[140:141], v[120:121], 0, s[46:47]
	v_lshl_add_u64 v[142:143], v[120:121], 0, s[48:49]
	v_lshl_add_u64 v[144:145], v[120:121], 0, s[50:51]
	v_lshl_add_u64 v[146:147], s[18:19], 0, v[2:3]
	v_lshl_add_u64 v[150:151], s[44:45], 0, v[2:3]
	v_lshl_add_u64 v[156:157], s[4:5], 0, v[2:3]
	s_lshl_b64 s[10:11], s[28:29], 14
	s_mov_b32 s17, 0
	s_movk_i32 s13, 0x1000
	v_mov_b32_e32 v1, 0x358637bd
	s_mov_b32 s18, 0xf800000
	v_mov_b32_e32 v160, 0x260
	v_mov_b32_e32 v161, 0x39800000
	s_branch .LBB0_46
